# no grid barrier between outproj(half 0) and in-proj(half 1): the two phases share no data
# baseline (speedup 1.0000x reference)
; __global__ void __launch_bounds__(512) mega_kernel(Params p, int ph_begin, int ph_end) {
;     ...
;   for (int ph = ph_begin; ph < ph_end; ++ph) {
;     run_phase(p, ph, smem);
;     if (ph + 1 < ph_end) {
;       if (ph == ph_begin) cg::this_grid().sync();
;       else xcd_barrier(bar, xcc, st);
;     }
.LBB0_546:
	s_add_i32 s16, s81, 1
	s_cmp_ge_i32 s16, s35
	s_mov_b64 s[0:1], -1
	s_cbranch_scc1 .LBB0_10
	s_cmp_eq_u32 s81, 6
	s_cbranch_scc1 .LBB0_9
	s_cmp_eq_u32 s81, 17
	s_cbranch_scc1 .LBB0_9
	s_waitcnt vmcnt(0)
	s_waitcnt vmcnt(0) lgkmcnt(0)
	s_barrier
	s_mov_b64 s[0:1], exec
	v_readlane_b32 s2, v242, 9
	v_readlane_b32 s3, v242, 10
	s_and_b64 s[2:3], s[0:1], s[2:3]
	s_mov_b64 exec, s[2:3]
	s_cbranch_execz .LBB0_600
	v_readlane_b32 s2, v240, 5
	s_waitcnt vmcnt(0) expcnt(0) lgkmcnt(0)
	s_nop 0
	v_mov_b32_e32 v0, s2
	ds_read_b32 v2, v0
	v_readlane_b32 s2, v240, 6
	s_waitcnt lgkmcnt(0)
	v_cmp_ne_u32_e32 vcc, 0, v2
	v_mov_b32_e32 v0, s2
	ds_read_b32 v0, v0
	s_cbranch_vccnz .LBB0_564
	s_mov_b32 s8, 1
	s_branch .LBB0_552
